# g5 plus phase_odd_rows load de-serialisation: c_kv load hoisted above the c_q reduction, rope-table loads of the k_da and k_r sections issued together with counted vmcnt
# speedup vs baseline: 1.0040x; 1.0040x over previous
; __device__ __forceinline__ unsigned pk2(float lo, float hi) { unsigned r; asm("v_cvt_pk_bf16_f32 %0, %1, %2" : "=v"(r) : "v"(lo), "v"(hi)); return r; }
; __device__ __forceinline__ float bflo(unsigned u) { return __uint_as_float(u << 16); }
; __device__ __forceinline__ float bfhi(unsigned u) { return __uint_as_float(u & 0xffff0000u); }
; __device__ __forceinline__ void phase_odd_rows(const Params& p, int o, int grp) {
;     ...
;         {
;             u32x4 v = {0u, 0u, 0u, 0u}; if (lane < 48) v = *(const u32x4*)(ur + 2048 + lane * 8);
;             float x[8] = {bflo(v.x), bfhi(v.x), bflo(v.y), bfhi(v.y), bflo(v.z), bfhi(v.z), bflo(v.w), bfhi(v.w)};
;             float ss = 0.f;
; #pragma unroll
;             for (int j = 0; j < 8; ++j) ss += x[j] * x[j];
;             const float r = rsqrtf(wave_sum(ss) * (1.f / 384.f) + EPS);
;             if (lane < 48) { u32x4 ov; ov.x = pk2(x[0] * r * gqa[0], x[1] * r * gqa[1]); ov.y = pk2(x[2] * r * gqa[2], x[3] * r * gqa[3]); ov.z = pk2(x[4] * r * gqb[0], x[5] * r * gqb[1]); ov.w = pk2(x[6] * r * gqb[2], x[7] * r * gqb[3]);
;                 *(u32x4*)(ur + 2048 + lane * 8) = ov; }
;         }
;         {
;             u32x4 v = {0u, 0u, 0u, 0u}; if (lane < 32) v = *(const u32x4*)(ur + 2432 + lane * 8);
;             float x[8] = {bflo(v.x), bfhi(v.x), bflo(v.y), bfhi(v.y), bflo(v.z), bfhi(v.z), bflo(v.w), bfhi(v.w)};
;             float ss = 0.f;
; #pragma unroll
;             for (int j = 0; j < 8; ++j) ss += x[j] * x[j];
;             const float r = rsqrtf(wave_sum(ss) * (1.f / 256.f) + EPS);
;             if (lane < 32) { u32x4 ov; ov.x = pk2(x[0] * r * gka[0], x[1] * r * gka[1]); ov.y = pk2(x[2] * r * gka[2], x[3] * r * gka[3]); ov.z = pk2(x[4] * r * gkb[0], x[5] * r * gkb[1]); ov.w = pk2(x[6] * r * gkb[2], x[7] * r * gkb[3]);
;                 *(u32x4*)(ur + 2432 + lane * 8) = ov; }
;         }
.LBB0_571:
	s_or_b64 exec, exec, s[12:13]
	v_mov_b32_e32 v68, 0
	v_mov_b32_e32 v69, 0
	v_mov_b32_e32 v70, 0
	v_mov_b32_e32 v71, 0
	s_and_saveexec_b64 s[12:13], s[4:5]
	v_add_co_u32_e32 v72, vcc, 0x13ad9000, v20
	s_nop 1
	v_addc_co_u32_e32 v73, vcc, 0, v21, vcc
	global_load_dwordx4 v[68:71], v[72:73], off offset:2560
	s_or_b64 exec, exec, s[12:13]
	s_waitcnt vmcnt(1)
	v_and_b32_e32 v33, 0xffff0000, v16
	v_lshlrev_b32_e32 v42, 16, v16
	v_lshlrev_b32_e32 v32, 16, v17
	v_and_b32_e32 v23, 0xffff0000, v17
	v_lshlrev_b32_e32 v17, 16, v19
	v_and_b32_e32 v16, 0xffff0000, v19
	v_mul_f32_e32 v19, v33, v33
	v_fmac_f32_e32 v19, v42, v42
	v_fmac_f32_e32 v19, v32, v32
	v_lshlrev_b32_e32 v22, 16, v18
	v_fmac_f32_e32 v19, v23, v23
	v_and_b32_e32 v18, 0xffff0000, v18
	v_fmac_f32_e32 v19, v22, v22
	v_fmac_f32_e32 v19, v18, v18
	v_fmac_f32_e32 v19, v17, v17
	v_fmac_f32_e32 v19, v16, v16
	ds_bpermute_b32 v43, v35, v19
	s_waitcnt lgkmcnt(0)
	v_add_f32_e32 v19, v19, v43
	ds_bpermute_b32 v43, v36, v19
	s_waitcnt lgkmcnt(0)
	v_add_f32_e32 v19, v19, v43
	ds_bpermute_b32 v43, v37, v19
	s_waitcnt lgkmcnt(0)
	v_add_f32_e32 v19, v19, v43
	ds_bpermute_b32 v43, v38, v19
	s_waitcnt lgkmcnt(0)
	v_add_f32_e32 v19, v19, v43
	ds_bpermute_b32 v43, v39, v19
	s_waitcnt lgkmcnt(0)
	v_add_f32_e32 v19, v19, v43
	ds_bpermute_b32 v43, v40, v19
	s_and_saveexec_b64 s[12:13], s[0:1]
	s_cbranch_execz .LBB0_573
	s_waitcnt lgkmcnt(0)
	v_add_f32_e32 v19, v19, v43
	v_fmamk_f32 v19, v19, 0x3b2aaaab, v195
	v_mul_f32_e32 v43, 0x4b800000, v19
	v_cmp_gt_f32_e32 vcc, s41, v19
	s_nop 1
	v_cndmask_b32_e32 v19, v19, v43, vcc
	v_rsq_f32_e32 v19, v19
	s_nop 0
	v_mul_f32_e32 v43, 0x45800000, v19
	v_cndmask_b32_e32 v19, v19, v43, vcc
	v_mul_f32_e32 v16, v19, v16
	v_mul_f32_e32 v17, v19, v17
	v_mul_f32_e32 v16, v11, v16
	v_mul_f32_e32 v42, v19, v42
	v_mul_f32_e32 v17, v10, v17
	v_cvt_pk_bf16_f32 v45, v17, v16
	v_add_co_u32_e32 v16, vcc, 0x13ad9000, v20
	v_mul_f32_e32 v33, v19, v33
	v_mul_f32_e32 v42, v4, v42
	v_mul_f32_e32 v32, v19, v32
	v_mul_f32_e32 v23, v19, v23
	v_mul_f32_e32 v22, v19, v22
	v_mul_f32_e32 v18, v19, v18
	v_addc_co_u32_e32 v17, vcc, 0, v21, vcc
	v_mul_f32_e32 v33, v5, v33
	v_cvt_pk_bf16_f32 v42, v42, v33
	v_mul_f32_e32 v32, v6, v32
	v_mul_f32_e32 v23, v7, v23
	v_cvt_pk_bf16_f32 v43, v32, v23
	v_mul_f32_e32 v22, v8, v22
	v_mul_f32_e32 v18, v9, v18
	v_cvt_pk_bf16_f32 v44, v22, v18
	global_store_dwordx4 v[16:17], v[42:45], off offset:1792
.LBB0_573:
	s_or_b64 exec, exec, s[12:13]
	s_waitcnt vmcnt(0)
	v_mov_b32_e32 v16, v68
	v_mov_b32_e32 v17, v69
	v_mov_b32_e32 v18, v70
	v_mov_b32_e32 v19, v71
.LBB0_575:
	v_and_b32_e32 v33, 0xffff0000, v16
	v_lshlrev_b32_e32 v42, 16, v16
	v_lshlrev_b32_e32 v32, 16, v17
	v_and_b32_e32 v23, 0xffff0000, v17
	v_lshlrev_b32_e32 v17, 16, v19
	v_and_b32_e32 v16, 0xffff0000, v19
	v_mul_f32_e32 v19, v33, v33
	v_fmac_f32_e32 v19, v42, v42
	v_fmac_f32_e32 v19, v32, v32
	v_lshlrev_b32_e32 v22, 16, v18
	v_fmac_f32_e32 v19, v23, v23
	v_and_b32_e32 v18, 0xffff0000, v18
	v_fmac_f32_e32 v19, v22, v22
	v_fmac_f32_e32 v19, v18, v18
	v_fmac_f32_e32 v19, v17, v17
	v_fmac_f32_e32 v19, v16, v16
	s_waitcnt lgkmcnt(0)
	ds_bpermute_b32 v43, v35, v19
	s_waitcnt lgkmcnt(0)
	v_add_f32_e32 v19, v19, v43
	ds_bpermute_b32 v43, v36, v19
	s_waitcnt lgkmcnt(0)
	v_add_f32_e32 v19, v19, v43
	ds_bpermute_b32 v43, v37, v19
	s_waitcnt lgkmcnt(0)
	v_add_f32_e32 v19, v19, v43
	ds_bpermute_b32 v43, v38, v19
	s_waitcnt lgkmcnt(0)
	v_add_f32_e32 v19, v19, v43
	ds_bpermute_b32 v43, v39, v19
	s_waitcnt lgkmcnt(0)
	v_add_f32_e32 v19, v19, v43
	ds_bpermute_b32 v43, v40, v19
	s_and_saveexec_b64 s[12:13], s[4:5]
	s_cbranch_execz .LBB0_577
	s_waitcnt lgkmcnt(0)
	v_add_f32_e32 v19, v19, v43
	v_fmamk_f32 v19, v19, 0x3b800000, v195
	v_mul_f32_e32 v43, 0x4b800000, v19
	v_cmp_gt_f32_e32 vcc, s41, v19
	s_nop 1
	v_cndmask_b32_e32 v19, v19, v43, vcc
	v_rsq_f32_e32 v19, v19
	s_nop 0
	v_mul_f32_e32 v43, 0x45800000, v19
	v_cndmask_b32_e32 v19, v19, v43, vcc
	v_mul_f32_e32 v16, v19, v16
	v_mul_f32_e32 v17, v19, v17
	v_mul_f32_e32 v16, v3, v16
	v_mul_f32_e32 v42, v19, v42
	v_mul_f32_e32 v17, v2, v17
	v_cvt_pk_bf16_f32 v45, v17, v16
	v_add_co_u32_e32 v16, vcc, 0x13ad9000, v20
	v_mul_f32_e32 v33, v19, v33
	v_mul_f32_e32 v42, v12, v42
	v_mul_f32_e32 v32, v19, v32
	v_mul_f32_e32 v23, v19, v23
	v_mul_f32_e32 v22, v19, v22
	v_mul_f32_e32 v18, v19, v18
	v_addc_co_u32_e32 v17, vcc, 0, v21, vcc
	v_mul_f32_e32 v33, v13, v33
	v_cvt_pk_bf16_f32 v42, v42, v33
	v_mul_f32_e32 v32, v14, v32
	v_mul_f32_e32 v23, v15, v23
	v_cvt_pk_bf16_f32 v43, v32, v23
	v_mul_f32_e32 v22, v0, v22
	v_mul_f32_e32 v18, v1, v18
	v_cvt_pk_bf16_f32 v44, v22, v18
	global_store_dwordx4 v[16:17], v[42:45], off offset:2560
; __device__ __forceinline__ unsigned pk2(float lo, float hi) { unsigned r; asm("v_cvt_pk_bf16_f32 %0, %1, %2" : "=v"(r) : "v"(lo), "v"(hi)); return r; }
; __device__ __forceinline__ float bflo(unsigned u) { return __uint_as_float(u << 16); }
; __device__ __forceinline__ float bfhi(unsigned u) { return __uint_as_float(u & 0xffff0000u); }
; __device__ __forceinline__ void phase_odd_rows(const Params& p, int o, int grp) {
;     ...
;         const int key = lr % KEYS; const bool lat = key >= CTXL; const int t = key - CTXL, prow = t >> 6, pcol = t & 63;
;     ...
;         if (lat) {
;             const int cmb = lane >> 1, hf = lane & 1, ax = cmb & 1, i1 = 1024 + (cmb >> 1) * 64 + ax * 32 + 8 * hf;
;             const u32x4 a = *(const u32x4*)(ur + i1), bq = *(const u32x4*)(ur + i1 + 16);
;             const float* tp = rt + ((ax ? pcol : prow) * 16 + 8 * hf) * 2;
;             u32x4 oa, ob;
; #pragma unroll
;             for (int q = 0; q < 4; ++q) {
;                 const f32x4 cs = *(const f32x4*)(tp + 4 * q);
;                 const float x1a = bflo(a[q]), x1b = bfhi(a[q]), x2a = bflo(bq[q]), x2b = bfhi(bq[q]);
;                 oa[q] = pk2(x1a * cs[0] - x2a * cs[1], x1b * cs[2] - x2b * cs[3]);
;                 ob[q] = pk2(x2a * cs[0] + x1a * cs[1], x2b * cs[2] + x1b * cs[3]);
;             }
;             *(u32x4*)(ur + i1) = oa; *(u32x4*)(ur + i1 + 16) = ob;
;         }
.LBB0_577:
	s_or_b64 exec, exec, s[12:13]
	s_mov_b32 s3, 0x3e0f83e1
	v_mul_hi_i32 v16, v34, s3
	v_lshrrev_b32_e32 v17, 31, v16
	v_ashrrev_i32_e32 v16, 11, v16
	v_add_u32_e32 v16, v16, v17
	v_mul_i32_i24_e32 v16, 0x2100, v16
	v_sub_u32_e32 v16, v34, v16
	s_movk_i32 s3, 0x100
	v_cmp_gt_i32_e64 s[12:13], s3, v16
	s_movk_i32 s3, 0xff
	v_add_u32_e32 v17, 0xffffff00, v16
	v_cmp_lt_i32_e32 vcc, s3, v16
	s_waitcnt lgkmcnt(0)
	v_ashrrev_i32_e32 v43, 6, v17
	v_and_b32_e32 v42, 63, v16
	s_and_saveexec_b64 s[34:35], vcc
	s_cbranch_execz .LBB0_579
	v_lshl_add_u64 v[16:17], v[26:27], 0, s[16:17]
	v_cndmask_b32_e64 v44, v42, v43, s[6:7]
	v_add_co_u32_e32 v32, vcc, 0x13ad8000, v16
	v_lshl_or_b32 v44, v44, 5, v41
	s_nop 0
	v_addc_co_u32_e32 v33, vcc, 0, v17, vcc
	v_ashrrev_i32_e32 v45, 31, v44
	global_load_dwordx4 v[16:19], v[32:33], off offset:3840
	global_load_dwordx4 v[20:23], v[32:33], off offset:3872
	v_lshl_add_u64 v[48:49], v[44:45], 2, s[64:65]
	global_load_dwordx4 v[44:47], v[48:49], off
	global_load_dwordx4 v[56:59], v[48:49], off offset:16
	global_load_dwordx4 v[60:63], v[48:49], off offset:32
	global_load_dwordx4 v[64:67], v[48:49], off offset:48
	s_waitcnt vmcnt(5)
	v_lshlrev_b32_e32 v51, 16, v16
	s_waitcnt vmcnt(4)
	v_lshlrev_b32_e32 v50, 16, v20
	s_waitcnt vmcnt(3)
	v_pk_mul_f32 v[52:53], v[44:45], v[50:51] op_sel:[0,1] op_sel_hi:[1,0]
	v_pk_mul_f32 v[44:45], v[44:45], v[50:51]
	v_sub_f32_e32 v52, v52, v53
	v_add_f32_e32 v53, v45, v44
	v_and_b32_e32 v45, 0xffff0000, v16
	v_and_b32_e32 v44, 0xffff0000, v20
	v_pk_mul_f32 v[50:51], v[46:47], v[44:45] op_sel:[0,1] op_sel_hi:[1,0]
	v_pk_mul_f32 v[44:45], v[46:47], v[44:45]
	v_sub_f32_e32 v16, v50, v51
	v_add_f32_e32 v20, v45, v44
	v_lshlrev_b32_e32 v51, 16, v17
	v_lshlrev_b32_e32 v50, 16, v21
	v_cvt_pk_bf16_f32 v16, v52, v16
	v_cvt_pk_bf16_f32 v20, v53, v20
	s_waitcnt vmcnt(2)
	v_mov_b64_e32 v[44:45], v[56:57]
	v_mov_b64_e32 v[46:47], v[58:59]
	v_pk_mul_f32 v[52:53], v[44:45], v[50:51] op_sel:[0,1] op_sel_hi:[1,0]
	v_pk_mul_f32 v[44:45], v[44:45], v[50:51]
	v_sub_f32_e32 v52, v52, v53
	v_add_f32_e32 v53, v44, v45
	v_and_b32_e32 v45, 0xffff0000, v17
	v_and_b32_e32 v44, 0xffff0000, v21
	v_pk_mul_f32 v[50:51], v[46:47], v[44:45] op_sel:[0,1] op_sel_hi:[1,0]
	v_pk_mul_f32 v[44:45], v[46:47], v[44:45]
	v_sub_f32_e32 v17, v50, v51
	v_add_f32_e32 v21, v44, v45
	v_lshlrev_b32_e32 v51, 16, v18
	v_lshlrev_b32_e32 v50, 16, v22
	v_cvt_pk_bf16_f32 v17, v52, v17
	v_cvt_pk_bf16_f32 v21, v53, v21
	s_waitcnt vmcnt(1)
	v_mov_b64_e32 v[44:45], v[60:61]
	v_mov_b64_e32 v[46:47], v[62:63]
	v_pk_mul_f32 v[52:53], v[44:45], v[50:51] op_sel:[0,1] op_sel_hi:[1,0]
	v_pk_mul_f32 v[44:45], v[44:45], v[50:51]
	v_sub_f32_e32 v52, v52, v53
	v_add_f32_e32 v53, v44, v45
	v_and_b32_e32 v45, 0xffff0000, v18
	v_and_b32_e32 v44, 0xffff0000, v22
	v_pk_mul_f32 v[50:51], v[46:47], v[44:45] op_sel:[0,1] op_sel_hi:[1,0]
	v_pk_mul_f32 v[44:45], v[46:47], v[44:45]
	v_sub_f32_e32 v18, v50, v51
	v_add_f32_e32 v22, v44, v45
	v_lshlrev_b32_e32 v49, 16, v19
	v_lshlrev_b32_e32 v48, 16, v23
	v_cvt_pk_bf16_f32 v18, v52, v18
	v_cvt_pk_bf16_f32 v22, v53, v22
	s_waitcnt vmcnt(0)
	v_mov_b64_e32 v[44:45], v[64:65]
	v_mov_b64_e32 v[46:47], v[66:67]
	v_pk_mul_f32 v[50:51], v[44:45], v[48:49] op_sel:[0,1] op_sel_hi:[1,0]
	v_pk_mul_f32 v[44:45], v[44:45], v[48:49]
	v_sub_f32_e32 v50, v50, v51
	v_add_f32_e32 v51, v44, v45
	v_and_b32_e32 v45, 0xffff0000, v19
	v_and_b32_e32 v44, 0xffff0000, v23
	v_pk_mul_f32 v[48:49], v[46:47], v[44:45] op_sel:[0,1] op_sel_hi:[1,0]
	v_pk_mul_f32 v[44:45], v[46:47], v[44:45]
	v_sub_f32_e32 v19, v48, v49
	v_cvt_pk_bf16_f32 v19, v50, v19
	v_add_f32_e32 v23, v44, v45
	v_cvt_pk_bf16_f32 v23, v51, v23
	global_store_dwordx4 v[32:33], v[16:19], off offset:3840
	global_store_dwordx4 v[32:33], v[20:23], off offset:3872
; __device__ __forceinline__ unsigned pk2(float lo, float hi) { unsigned r; asm("v_cvt_pk_bf16_f32 %0, %1, %2" : "=v"(r) : "v"(lo), "v"(hi)); return r; }
; __device__ __forceinline__ float bflo(unsigned u) { return __uint_as_float(u << 16); }
; __device__ __forceinline__ float bfhi(unsigned u) { return __uint_as_float(u & 0xffff0000u); }
; __device__ __forceinline__ void phase_odd_rows(const Params& p, int o, int grp) {
;     ...
;         if (lane < 2) {
;             const int ax = lane;
;             const u32x4 a = *(const u32x4*)(ur + 2688 + 16 * ax), bq = *(const u32x4*)(ur + 2688 + 16 * ax + 8);
;             u32x4 oa = a, ob = bq;
;             if (lat) {
;                 const float* tp = rt + ((ax ? pcol : prow) * 16) * 2;
; #pragma unroll
;                 for (int q = 0; q < 4; ++q) {
;                     const f32x4 c0 = *(const f32x4*)(tp + 8 * q), c1 = *(const f32x4*)(tp + 8 * q + 4);
;                     const float x1a = bflo(a[q]), x1b = bfhi(a[q]), x2a = bflo(bq[q]), x2b = bfhi(bq[q]);
;                     oa[q] = pk2(x1a * c0[0] - x2a * c0[1], x1b * c1[0] - x2b * c1[1]);
;                     ob[q] = pk2(x2a * c0[0] + x1a * c0[1], x2b * c1[0] + x1b * c1[1]);
;                 }
;             }
; #pragma unroll
;             for (int h = 0; h < 8; ++h) { bf16_t* kp = KM + (size_t)lr * 768 + h * 96 + 64 + 16 * ax; *(u32x4*)kp = oa; *(u32x4*)(kp + 8) = ob; }
.LBB0_579:
	s_or_b64 exec, exec, s[34:35]
	s_and_saveexec_b64 s[34:35], s[8:9]
	s_cbranch_execz .LBB0_568
	v_lshl_add_u64 v[16:17], v[24:25], 0, s[16:17]
	s_mov_b64 s[14:15], 0x13ad9c00
	v_lshl_add_u64 v[20:21], v[16:17], 0, s[14:15]
	v_add_co_u32_e32 v16, vcc, 0x13ad9000, v16
	s_nop 1
	v_addc_co_u32_e32 v17, vcc, 0, v17, vcc
	global_load_dwordx4 v[16:19], v[16:17], off offset:3072
	s_nop 0
	global_load_dwordx4 v[20:23], v[20:21], off offset:16
	s_and_saveexec_b64 s[14:15], s[12:13]
	s_xor_b64 s[12:13], exec, s[14:15]
	s_andn2_saveexec_b64 s[12:13], s[12:13]
	s_cbranch_execz .LBB0_567
	v_cndmask_b32_e64 v32, v42, v43, s[10:11]
	v_lshlrev_b32_e32 v32, 5, v32
	v_ashrrev_i32_e32 v33, 31, v32
	v_lshl_add_u64 v[32:33], v[32:33], 2, s[64:65]
	global_load_dwordx2 v[42:43], v[32:33], off
	global_load_dwordx2 v[44:45], v[32:33], off offset:16
	global_load_dwordx2 v[74:75], v[32:33], off offset:32
	global_load_dwordx2 v[76:77], v[32:33], off offset:48
	global_load_dwordx2 v[78:79], v[32:33], off offset:64
	global_load_dwordx2 v[80:81], v[32:33], off offset:80
	global_load_dwordx2 v[82:83], v[32:33], off offset:96
	global_load_dwordx2 v[84:85], v[32:33], off offset:112
	s_waitcnt vmcnt(9)
	v_lshlrev_b32_e32 v47, 16, v16
	s_waitcnt vmcnt(8)
	v_lshlrev_b32_e32 v46, 16, v20
	s_waitcnt vmcnt(7)
	v_pk_mul_f32 v[48:49], v[42:43], v[46:47] op_sel:[0,1] op_sel_hi:[1,0]
	v_pk_mul_f32 v[42:43], v[42:43], v[46:47]
	v_sub_f32_e32 v48, v48, v49
	v_add_f32_e32 v49, v42, v43
	v_and_b32_e32 v43, 0xffff0000, v16
	v_and_b32_e32 v42, 0xffff0000, v20
	s_waitcnt vmcnt(6)
	v_pk_mul_f32 v[46:47], v[44:45], v[42:43] op_sel:[0,1] op_sel_hi:[1,0]
	v_pk_mul_f32 v[42:43], v[44:45], v[42:43]
	v_sub_f32_e32 v16, v46, v47
	v_add_f32_e32 v20, v42, v43
	v_lshlrev_b32_e32 v47, 16, v17
	v_lshlrev_b32_e32 v46, 16, v21
	v_cvt_pk_bf16_f32 v16, v48, v16
	v_cvt_pk_bf16_f32 v20, v49, v20
	s_waitcnt vmcnt(5)
	v_mov_b64_e32 v[42:43], v[74:75]
	v_pk_mul_f32 v[48:49], v[42:43], v[46:47] op_sel:[0,1] op_sel_hi:[1,0]
	v_pk_mul_f32 v[42:43], v[42:43], v[46:47]
	v_sub_f32_e32 v48, v48, v49
	v_add_f32_e32 v49, v42, v43
	v_and_b32_e32 v43, 0xffff0000, v17
	v_and_b32_e32 v42, 0xffff0000, v21
	s_waitcnt vmcnt(4)
	v_mov_b64_e32 v[44:45], v[76:77]
	v_pk_mul_f32 v[46:47], v[44:45], v[42:43] op_sel:[0,1] op_sel_hi:[1,0]
	v_pk_mul_f32 v[42:43], v[44:45], v[42:43]
	v_sub_f32_e32 v17, v46, v47
	v_add_f32_e32 v21, v42, v43
	v_lshlrev_b32_e32 v47, 16, v18
	v_lshlrev_b32_e32 v46, 16, v22
	v_cvt_pk_bf16_f32 v17, v48, v17
	v_cvt_pk_bf16_f32 v21, v49, v21
	s_waitcnt vmcnt(3)
	v_mov_b64_e32 v[42:43], v[78:79]
	v_pk_mul_f32 v[48:49], v[42:43], v[46:47] op_sel:[0,1] op_sel_hi:[1,0]
	v_pk_mul_f32 v[42:43], v[42:43], v[46:47]
	v_sub_f32_e32 v48, v48, v49
	v_add_f32_e32 v49, v42, v43
	v_and_b32_e32 v43, 0xffff0000, v18
	v_and_b32_e32 v42, 0xffff0000, v22
	s_waitcnt vmcnt(2)
	v_mov_b64_e32 v[44:45], v[80:81]
	v_pk_mul_f32 v[46:47], v[44:45], v[42:43] op_sel:[0,1] op_sel_hi:[1,0]
	v_pk_mul_f32 v[42:43], v[44:45], v[42:43]
	v_lshlrev_b32_e32 v45, 16, v23
	v_add_f32_e32 v22, v42, v43
	s_nop 0
	v_lshlrev_b32_e32 v44, 16, v19
	v_sub_f32_e32 v18, v46, v47
	v_cvt_pk_bf16_f32 v18, v48, v18
	v_cvt_pk_bf16_f32 v22, v49, v22
	s_waitcnt vmcnt(1)
	v_mov_b64_e32 v[42:43], v[82:83]
	v_pk_mul_f32 v[46:47], v[42:43], v[44:45]
	s_nop 0
	v_sub_f32_e32 v50, v46, v47
	v_and_b32_e32 v47, 0xffff0000, v23
	v_and_b32_e32 v46, 0xffff0000, v19
	s_waitcnt vmcnt(0)
	v_mov_b64_e32 v[32:33], v[84:85]
	v_pk_mul_f32 v[48:49], v[32:33], v[46:47]
	v_pk_mul_f32 v[42:43], v[42:43], v[44:45] op_sel:[0,1] op_sel_hi:[1,0]
	v_sub_f32_e32 v19, v48, v49
	v_add_f32_e32 v23, v42, v43
	v_pk_mul_f32 v[32:33], v[32:33], v[46:47] op_sel:[0,1] op_sel_hi:[1,0]
	v_cvt_pk_bf16_f32 v19, v50, v19
	s_nop 0
	v_add_f32_e32 v32, v32, v33
	v_cvt_pk_bf16_f32 v23, v23, v32
	s_branch .LBB0_567
